# v23 plus: odin indexer-q rope epilogue loop touches the wave's cos/sin block once before the row loop so per-row table loads hit L1
# speedup vs baseline: 1.0097x; 1.0021x over previous
.LBB0_479:
	s_or_b64 exec, exec, s[4:5]
	v_mov_b32_e32 v134, v208
	v_mov_b32_e32 v1, v208
	s_mov_b64 s[4:5], -1
	s_and_b64 vcc, exec, s[2:3]
	s_waitcnt lgkmcnt(0)
	s_barrier
	s_cbranch_vccz .LBB0_493
	s_and_b64 vcc, exec, s[8:9]
	s_cbranch_vccz .LBB0_489
	s_and_b64 vcc, exec, s[10:11]
	s_cbranch_vccz .LBB0_485
	v_ashrrev_i32_e32 v142, 1, v1
	v_and_b32_e32 v143, 0xffffffe0, v142
	v_add_lshl_u32 v130, v143, s57, 4
	v_ashrrev_i32_e32 v131, 31, v130
	v_lshlrev_b64 v[130:131], 2, v[130:131]
	v_lshlrev_b32_e32 v1, 3, v134
	v_lshl_add_u64 v[132:133], s[16:17], 0, v[130:131]
	v_and_b32_e32 v140, 56, v1
	v_mov_b32_e32 v141, v0
	v_lshl_add_u64 v[132:133], v[132:133], 0, v[140:141]
	v_lshl_add_u64 v[130:131], s[18:19], 0, v[130:131]
	v_lshl_add_u64 v[130:131], v[130:131], 0, v[140:141]
	global_load_dwordx2 v[136:137], v[132:133], off
	global_load_dwordx2 v[138:139], v[130:131], off
	v_and_b32_e32 v222, 63, v208
	v_mov_b32_e32 v223, 0
	v_lshlrev_b32_e32 v222, 5, v222
	v_lshl_add_u64 v[224:225], v[132:133], 0, v[222:223]
	v_lshl_add_u64 v[226:227], v[130:131], 0, v[222:223]
	global_load_dword v228, v[224:225], off
	global_load_dword v229, v[226:227], off
	s_lshl_b32 s6, s84, 1
	v_and_b32_e32 v144, 63, v134
	v_and_b32_e32 v145, 31, v134
	v_lshl_add_u64 v[130:131], s[16:17], 0, v[140:141]
	v_lshl_add_u64 v[132:133], s[18:19], 0, v[140:141]
	v_bfe_u32 v140, v134, 5, 1
	v_add_u32_e32 v134, s26, v143
	s_add_i32 s6, s6, s60
	v_ashrrev_i32_e32 v135, 31, v134
	v_add_u32_e32 v140, s6, v140
	v_xor_b32_e32 v1, 8, v215
	v_lshlrev_b64 v[134:135], 11, v[134:135]
	v_lshlrev_b64 v[140:141], 7, v[140:141]
	v_cmp_lt_i32_e32 vcc, v1, v217
	v_lshl_add_u64 v[134:135], v[134:135], 0, v[140:141]
	v_lshrrev_b32_e32 v140, 5, v142
	s_movk_i32 s6, 0x4080
	v_cndmask_b32_e32 v1, v215, v1, vcc
	v_lshl_or_b32 v134, v145, 2, v134
	v_mul_lo_u32 v140, v140, s6
	v_lshlrev_b32_e32 v1, 2, v1
	v_cmp_gt_u32_e32 vcc, 8, v145
	v_cmp_gt_u32_e64 s[4:5], 16, v145
	v_lshl_add_u64 v[134:135], s[22:23], 0, v[134:135]
	v_lshl_add_u32 v140, v144, 3, v140
	v_add_u32_e32 v141, s27, v143
	s_movk_i32 s70, 0xbf80
